# phase 0: RoPE table computed by the last workgroup (one modulation item) instead of workgroup 0 (two items)
# baseline (speedup 1.0000x reference)
.LBB0_15:
	s_or_b64 exec, exec, s[0:1]
	v_readlane_b32 s0, v247, 0
	v_mov_b32_e32 v0, v187
	s_cmp_eq_u32 s0, 0x1ff
	s_movk_i32 s2, 0x400
	s_cselect_b64 s[0:1], -1, 0
	v_cmp_gt_i32_e32 vcc, s2, v0
	s_and_b64 s[2:3], s[0:1], vcc
	s_and_saveexec_b64 s[0:1], s[2:3]
	s_cbranch_execz .LBB0_26
	v_and_b32_e32 v1, 15, v0
	v_cvt_f64_u32_e32 v[2:3], v1
	v_ldexp_f64 v[4:5], v[2:3], -4
	v_mov_b32_e32 v1, 0x40c38800
	v_mov_b32_e32 v2, 0x3ff00000
	v_cmp_eq_f64_e32 vcc, 0, v[4:5]
	v_mov_b32_e32 v3, 0
	v_mov_b32_e32 v6, v3
	v_cndmask_b32_e32 v7, v1, v2, vcc
	v_frexp_exp_i32_f64_e32 v1, v[6:7]
	v_frexp_mant_f64_e32 v[6:7], v[6:7]
	s_mov_b32 s3, 0x3fe55555
	s_mov_b32 s2, 0x55555555
	v_cmp_gt_f64_e32 vcc, s[2:3], v[6:7]
	s_mov_b32 s6, 0x4222de17
	s_mov_b32 s7, 0x3fbdee67
	v_cndmask_b32_e64 v2, 0, 1, vcc
	v_ldexp_f64 v[6:7], v[6:7], v2
	v_add_f64 v[8:9], v[6:7], 1.0
	v_rcp_f64_e32 v[10:11], v[8:9]
	v_add_f64 v[14:15], v[8:9], -1.0
	v_add_f64 v[12:13], v[6:7], -1.0
	v_add_f64 v[6:7], v[6:7], -v[14:15]
	v_fma_f64 v[14:15], -v[8:9], v[10:11], 1.0
	v_fmac_f64_e32 v[10:11], v[14:15], v[10:11]
	v_fma_f64 v[14:15], -v[8:9], v[10:11], 1.0
	v_fmac_f64_e32 v[10:11], v[14:15], v[10:11]
	v_mul_f64 v[14:15], v[12:13], v[10:11]
	v_mul_f64 v[16:17], v[8:9], v[14:15]
	v_fma_f64 v[8:9], v[14:15], v[8:9], -v[16:17]
	v_fmac_f64_e32 v[8:9], v[14:15], v[6:7]
	v_add_f64 v[6:7], v[16:17], v[8:9]
	v_add_f64 v[18:19], v[12:13], -v[6:7]
	v_add_f64 v[16:17], v[6:7], -v[16:17]
	v_add_f64 v[12:13], v[12:13], -v[18:19]
	v_add_f64 v[6:7], v[12:13], -v[6:7]
	v_add_f64 v[8:9], v[16:17], -v[8:9]
	v_add_f64 v[6:7], v[8:9], v[6:7]
	v_add_f64 v[6:7], v[18:19], v[6:7]
	v_mul_f64 v[6:7], v[10:11], v[6:7]
	v_add_f64 v[8:9], v[14:15], v[6:7]
	v_add_f64 v[10:11], v[8:9], -v[14:15]
	v_add_f64 v[6:7], v[6:7], -v[10:11]
	v_mul_f64 v[10:11], v[8:9], v[8:9]
	v_fma_f64 v[12:13], v[8:9], v[8:9], -v[10:11]
	v_add_f64 v[14:15], v[6:7], v[6:7]
	v_fmac_f64_e32 v[12:13], v[8:9], v[14:15]
	v_add_f64 v[14:15], v[10:11], v[12:13]
	v_add_f64 v[10:11], v[14:15], -v[10:11]
	v_add_f64 v[10:11], v[12:13], -v[10:11]
	v_mov_b32_e32 v12, 0x968915a9
	v_mov_b32_e32 v13, 0x3fba6564
	v_fmac_f64_e32 v[12:13], s[6:7], v[14:15]
	v_mov_b32_e32 v16, 0x3abe935a
	v_mov_b32_e32 v17, 0x3fbe25e4
	v_fmac_f64_e32 v[16:17], v[14:15], v[12:13]
	v_mov_b32_e32 v12, 0x47e6c9c2
	v_mov_b32_e32 v13, 0x3fc110ef
	v_fmac_f64_e32 v[12:13], v[14:15], v[16:17]
	v_mov_b32_e32 v16, 0xcfa74449
	v_mov_b32_e32 v17, 0x3fc3b13b
	v_fmac_f64_e32 v[16:17], v[14:15], v[12:13]
	v_mov_b32_e32 v12, 0x71bf3c30
	v_mov_b32_e32 v13, 0x3fc745d1
	v_fmac_f64_e32 v[12:13], v[14:15], v[16:17]
	v_mov_b32_e32 v16, 0x1c7792ce
	v_mov_b32_e32 v17, 0x3fcc71c7
	v_fmac_f64_e32 v[16:17], v[14:15], v[12:13]
	v_mov_b32_e32 v12, 0x924920da
	v_mov_b32_e32 v13, 0x3fd24924
	v_subbrev_co_u32_e32 v1, vcc, 0, v1, vcc
	v_fmac_f64_e32 v[12:13], v[14:15], v[16:17]
	v_mov_b32_e32 v16, 0x9999999c
	v_mov_b32_e32 v17, 0x3fd99999
	v_fmac_f64_e32 v[16:17], v[14:15], v[12:13]
	v_cvt_f64_i32_e32 v[12:13], v1
	s_mov_b32 s7, 0x3fe62e42
	s_mov_b32 s6, 0xfefa39ef
	v_mul_f64 v[18:19], v[12:13], s[6:7]
	v_mul_f64 v[24:25], v[8:9], v[14:15]
	v_fma_f64 v[20:21], v[12:13], s[6:7], -v[18:19]
	s_mov_b32 s11, 0x3c7abc9e
	s_mov_b32 s10, 0x3b39803f
	v_fma_f64 v[26:27], v[14:15], v[8:9], -v[24:25]
	v_fmac_f64_e32 v[20:21], s[10:11], v[12:13]
	v_fmac_f64_e32 v[26:27], v[14:15], v[6:7]
	v_add_f64 v[12:13], v[18:19], v[20:21]
	v_fmac_f64_e32 v[26:27], v[10:11], v[8:9]
	v_add_f64 v[18:19], v[12:13], -v[18:19]
	v_ldexp_f64 v[22:23], v[6:7], 1
	v_add_f64 v[6:7], v[24:25], v[26:27]
	v_add_f64 v[18:19], v[20:21], -v[18:19]
	v_ldexp_f64 v[20:21], v[8:9], 1
	v_add_f64 v[8:9], v[6:7], -v[24:25]
	v_mul_f64 v[24:25], v[14:15], v[16:17]
	v_fma_f64 v[14:15], v[14:15], v[16:17], -v[24:25]
	v_fmac_f64_e32 v[14:15], v[10:11], v[16:17]
	v_add_f64 v[10:11], v[24:25], v[14:15]
	v_add_f64 v[16:17], v[10:11], -v[24:25]
	v_add_f64 v[14:15], v[14:15], -v[16:17]
	v_add_f64 v[16:17], v[10:11], s[2:3]
	s_mov_b32 s3, 0xbfe55555
	v_add_f64 v[24:25], v[16:17], s[2:3]
	s_mov_b32 s2, 0xd5df274d
	s_mov_b32 s3, 0x3c8543b0
	v_add_f64 v[10:11], v[10:11], -v[24:25]
	v_add_f64 v[14:15], v[14:15], s[2:3]
	v_add_f64 v[10:11], v[14:15], v[10:11]
	v_add_f64 v[14:15], v[16:17], v[10:11]
	v_add_f64 v[16:17], v[16:17], -v[14:15]
	v_add_f64 v[10:11], v[10:11], v[16:17]
	v_mul_f64 v[16:17], v[6:7], v[14:15]
	v_fma_f64 v[24:25], v[6:7], v[14:15], -v[16:17]
	v_add_f64 v[8:9], v[26:27], -v[8:9]
	v_fmac_f64_e32 v[24:25], v[6:7], v[10:11]
	v_fmac_f64_e32 v[24:25], v[8:9], v[14:15]
	v_add_f64 v[6:7], v[16:17], v[24:25]
	v_add_f64 v[8:9], v[6:7], -v[16:17]
	v_add_f64 v[10:11], v[20:21], v[6:7]
	v_add_f64 v[8:9], v[24:25], -v[8:9]
	v_add_f64 v[14:15], v[10:11], -v[20:21]
	v_add_f64 v[6:7], v[6:7], -v[14:15]
	v_add_f64 v[8:9], v[22:23], v[8:9]
	v_add_f64 v[6:7], v[8:9], v[6:7]
	v_add_f64 v[8:9], v[10:11], v[6:7]
	v_add_f64 v[10:11], v[8:9], -v[10:11]
	v_add_f64 v[6:7], v[6:7], -v[10:11]
	v_add_f64 v[10:11], v[12:13], v[8:9]
	v_add_f64 v[14:15], v[10:11], -v[12:13]
	v_add_f64 v[16:17], v[10:11], -v[14:15]
	v_add_f64 v[12:13], v[12:13], -v[16:17]
	v_add_f64 v[8:9], v[8:9], -v[14:15]
	v_add_f64 v[8:9], v[8:9], v[12:13]
	v_add_f64 v[12:13], v[18:19], v[6:7]
	v_add_f64 v[14:15], v[12:13], -v[18:19]
	v_add_f64 v[8:9], v[12:13], v[8:9]
	v_add_f64 v[16:17], v[12:13], -v[14:15]
	v_add_f64 v[12:13], v[10:11], v[8:9]
	v_add_f64 v[16:17], v[18:19], -v[16:17]
	v_add_f64 v[6:7], v[6:7], -v[14:15]
	v_add_f64 v[10:11], v[12:13], -v[10:11]
	v_add_f64 v[6:7], v[6:7], v[16:17]
	v_add_f64 v[8:9], v[8:9], -v[10:11]
	v_add_f64 v[6:7], v[6:7], v[8:9]
	v_add_f64 v[8:9], v[12:13], v[6:7]
	v_add_f64 v[10:11], v[8:9], -v[12:13]
	v_add_f64 v[6:7], v[6:7], -v[10:11]
	v_mul_f64 v[10:11], v[4:5], v[8:9]
	v_fma_f64 v[8:9], v[4:5], v[8:9], -v[10:11]
	v_fmac_f64_e32 v[8:9], v[4:5], v[6:7]
	s_movk_i32 s12, 0x204
	v_add_f64 v[6:7], v[10:11], v[8:9]
	v_cmp_class_f64_e64 vcc, v[10:11], s12
	s_mov_b32 s2, 0x652b82fe
	v_add_f64 v[12:13], v[6:7], -v[10:11]
	v_cndmask_b32_e32 v7, v7, v11, vcc
	v_cndmask_b32_e32 v6, v6, v10, vcc
	s_mov_b32 s3, 0x3ff71547
	v_mul_f64 v[10:11], v[6:7], s[2:3]
	v_rndne_f64_e32 v[10:11], v[10:11]
	s_mov_b32 s7, 0xbfe62e42
	v_add_f64 v[8:9], v[8:9], -v[12:13]
	v_fma_f64 v[12:13], s[6:7], v[10:11], v[6:7]
	s_mov_b32 s11, 0xbc7abc9e
	s_mov_b32 s2, 0x6a5dcb37
	v_fmac_f64_e32 v[12:13], s[10:11], v[10:11]
	v_mov_b32_e32 v14, 0xfca7ab0c
	v_mov_b32_e32 v15, 0x3e928af3
	s_mov_b32 s3, 0x3e5ade15
	v_fmac_f64_e32 v[14:15], s[2:3], v[12:13]
	v_mov_b32_e32 v16, 0x623fde64
	v_mov_b32_e32 v17, 0x3ec71dee
	v_fmac_f64_e32 v[16:17], v[12:13], v[14:15]
	v_mov_b32_e32 v14, 0x7c89e6b0
	v_mov_b32_e32 v15, 0x3efa0199
	v_fmac_f64_e32 v[14:15], v[12:13], v[16:17]
	v_mov_b32_e32 v16, 0x14761f6e
	v_mov_b32_e32 v17, 0x3f2a01a0
	v_fmac_f64_e32 v[16:17], v[12:13], v[14:15]
	v_mov_b32_e32 v14, 0x1852b7b0
	v_mov_b32_e32 v15, 0x3f56c16c
	v_fmac_f64_e32 v[14:15], v[12:13], v[16:17]
	v_mov_b32_e32 v16, 0x11122322
	v_mov_b32_e32 v17, 0x3f811111
	v_fmac_f64_e32 v[16:17], v[12:13], v[14:15]
	v_mov_b32_e32 v14, 0x555502a1
	v_mov_b32_e32 v15, 0x3fa55555
	s_mov_b32 s8, 0
	v_fmac_f64_e32 v[14:15], v[12:13], v[16:17]
	v_mov_b32_e32 v16, 0x55555511
	v_mov_b32_e32 v17, 0x3fc55555
	s_mov_b32 s9, 0x7ff00000
	v_fmac_f64_e32 v[16:17], v[12:13], v[14:15]
	v_mov_b32_e32 v14, 11
	v_mov_b32_e32 v15, 0x3fe00000
	s_mov_b32 s2, 0
	v_cmp_neq_f64_e64 vcc, |v[6:7]|, s[8:9]
	v_fmac_f64_e32 v[14:15], v[12:13], v[16:17]
	s_mov_b32 s3, 0x40900000
	v_cndmask_b32_e32 v9, 0, v9, vcc
	v_cndmask_b32_e32 v8, 0, v8, vcc
	v_fma_f64 v[14:15], v[12:13], v[14:15], 1.0
	v_cmp_nlt_f64_e32 vcc, s[2:3], v[6:7]
	s_mov_b32 s2, 0
	v_fma_f64 v[12:13], v[12:13], v[14:15], 1.0
	v_cvt_i32_f64_e32 v1, v[10:11]
	s_mov_b32 s3, 0xc090cc00
	v_ldexp_f64 v[10:11], v[12:13], v1
	v_mov_b32_e32 v1, 0x7ff00000
	v_cmp_ngt_f64_e64 s[6:7], s[2:3], v[6:7]
	v_cndmask_b32_e32 v1, v1, v11, vcc
	s_and_b64 vcc, s[6:7], vcc
	v_cndmask_b32_e64 v7, 0, v1, s[6:7]
	v_cndmask_b32_e32 v6, 0, v10, vcc
	v_mov_b64_e32 v[10:11], v[6:7]
	v_fmac_f64_e32 v[10:11], v[10:11], v[8:9]
	v_cmp_class_f64_e64 vcc, v[6:7], s12
	v_readlane_b32 s36, v247, 49
	v_ashrrev_i32_e32 v1, 31, v0
	v_cndmask_b32_e32 v7, v11, v7, vcc
	v_cndmask_b32_e32 v6, v10, v6, vcc
	v_and_b32_e32 v9, 0x7fffffff, v7
	v_mov_b32_e32 v8, v6
	v_div_scale_f64 v[10:11], s[2:3], v[8:9], v[8:9], 1.0
	v_rcp_f64_e32 v[12:13], v[10:11]
	v_div_scale_f64 v[8:9], vcc, 1.0, v[8:9], 1.0
	v_readlane_b32 s40, v247, 53
	v_fma_f64 v[14:15], -v[10:11], v[12:13], 1.0
	v_fmac_f64_e32 v[12:13], v[12:13], v[14:15]
	v_fma_f64 v[14:15], -v[10:11], v[12:13], 1.0
	v_fmac_f64_e32 v[12:13], v[12:13], v[14:15]
	v_mul_f64 v[14:15], v[8:9], v[12:13]
	v_fma_f64 v[8:9], -v[10:11], v[14:15], v[8:9]
	v_div_fmas_f64 v[8:9], v[8:9], v[12:13], v[14:15]
	v_div_fixup_f64 v[6:7], v[8:9], |v[6:7]|, 1.0
	v_cmp_neq_f64_e32 vcc, s[8:9], v[4:5]
	v_readlane_b32 s41, v247, 54
	v_readlane_b32 s37, v247, 50
	v_cndmask_b32_e32 v5, 0, v7, vcc
	v_cndmask_b32_e32 v4, 0, v6, vcc
	v_readlane_b32 s38, v247, 51
	v_readlane_b32 s39, v247, 52
	v_readlane_b32 s42, v247, 55
	v_lshl_add_u64 v[6:7], v[0:1], 2, s[40:41]
	s_mov_b64 s[6:7], 0x1000
	s_mov_b64 s[2:3], 0
	v_lshl_add_u64 v[6:7], v[6:7], 0, s[6:7]
	s_mov_b32 s34, 0xfe5163ab
	s_mov_b32 s35, 0x3c439041
	s_mov_b32 s36, 0xdb629599
	s_mov_b32 s37, 0xf534ddc0
	s_mov_b32 s38, 0xfc2757d1
	s_mov_b32 s39, 0x4e441529
	s_mov_b32 s40, 0xa2f9836e
	s_mov_b32 s41, 0x3fc90fda
	s_mov_b32 s42, 0xbfc90fda
	v_mov_b32_e32 v1, 0x3c0881c4
	v_mov_b32_e32 v8, 0xbab64f3b
	v_not_b32_e32 v9, 63
	v_not_b32_e32 v10, 31
	v_mov_b32_e32 v11, 0x7fc00000
	v_mov_b32_e32 v12, v0
	v_readlane_b32 s43, v247, 56
	v_readlane_b32 s44, v247, 57
	v_readlane_b32 s45, v247, 58
	v_readlane_b32 s46, v247, 59
	v_readlane_b32 s47, v247, 60
	v_readlane_b32 s48, v247, 61
	v_readlane_b32 s49, v247, 62
	v_readlane_b32 s50, v247, 63
	v_readlane_b32 s51, v246, 0
	s_branch .LBB0_18
